# strategy 4 variant: static s_setprio 1 for waves 0-3 (leading half) instead of 4-7
# baseline (speedup 1.0000x reference)
;     __host__ __device__ bool next(int i, Unit& u) const { return at((long)i * G + c, u); }
;     __host__ __device__ bool next(int i, Unit& u) const { if (i != 0 || c >= cnt) return false; u.pm = pm0 + c / nN; u.pn = c % nN; u.k0 = 0; u.nt = ntk; return true; }
;     ...
;         const bool has_next = S.next(ui + 1, nxt);
;         const char* nA = has_next ? (const char*)g.A + (size_t)nxt.pm * tstep + (size_t)nxt.k0 * (BK * 2) : cA; const char* nB = has_next ? (const char*)g.Bt + (size_t)nxt.pn * tstep + (size_t)nxt.k0 * (BK * 2) : cB;
;     ...
; #pragma unroll
;         for (int a = 0; a < 2; ++a)
; #pragma unroll
;             for (int b = 0; b < 2; ++b)
; #pragma unroll
;                 for (int m = 0; m < 4; ++m)
; #pragma unroll
;                     for (int n = 0; n < 2; ++n) acc[a][b][m][n] = (f32x4){0.f, 0.f, 0.f, 0.f};
.LBB0_118:
	s_ashr_i32 s29, s28, 31
	s_lshl_b64 s[30:31], s[28:29], 19
	s_add_u32 s30, s52, s30
	s_addc_u32 s31, s53, s31
	s_and_b64 s[34:35], s[0:1], exec
	s_cselect_b32 s5, s31, s9
	s_cselect_b32 s7, s30, s8
	s_ashr_i32 s27, s26, 31
	s_lshl_b64 s[34:35], s[26:27], 19
	s_add_u32 s34, s77, s34
	s_addc_u32 s35, s84, s35
	s_and_b64 s[38:39], s[0:1], exec
	s_cselect_b32 s27, s35, s37
	s_cselect_b32 s29, s34, s36
	s_add_u32 s8, s8, 0x40080
	s_addc_u32 s9, s9, 0
	s_add_u32 s58, s36, 0x100
	v_mov_b32_e32 v0, 0
	s_addc_u32 s59, s37, 0
	s_mov_b32 s78, -2
	v_mov_b32_e32 v1, v0
	v_mov_b32_e32 v2, v0
	v_mov_b32_e32 v3, v0
	v_mov_b32_e32 v4, v0
	v_mov_b32_e32 v5, v0
	v_mov_b32_e32 v6, v0
	v_mov_b32_e32 v7, v0
	v_mov_b32_e32 v16, v0
	v_mov_b32_e32 v17, v0
	v_mov_b32_e32 v18, v0
	v_mov_b32_e32 v19, v0
	v_mov_b32_e32 v20, v0
	v_mov_b32_e32 v21, v0
	v_mov_b32_e32 v22, v0
	v_mov_b32_e32 v23, v0
	v_mov_b32_e32 v32, v0
	v_mov_b32_e32 v33, v0
	v_mov_b32_e32 v34, v0
	v_mov_b32_e32 v35, v0
	v_mov_b32_e32 v36, v0
	v_mov_b32_e32 v37, v0
	v_mov_b32_e32 v38, v0
	v_mov_b32_e32 v39, v0
	v_mov_b32_e32 v56, v0
	v_mov_b32_e32 v57, v0
	v_mov_b32_e32 v58, v0
	v_mov_b32_e32 v59, v0
	v_mov_b32_e32 v60, v0
	v_mov_b32_e32 v61, v0
	v_mov_b32_e32 v62, v0
	v_mov_b32_e32 v63, v0
	v_mov_b32_e32 v8, v0
	v_mov_b32_e32 v9, v0
	v_mov_b32_e32 v10, v0
	v_mov_b32_e32 v11, v0
	v_mov_b32_e32 v12, v0
	v_mov_b32_e32 v13, v0
	v_mov_b32_e32 v14, v0
	v_mov_b32_e32 v15, v0
	v_mov_b32_e32 v24, v0
	v_mov_b32_e32 v25, v0
	v_mov_b32_e32 v26, v0
	v_mov_b32_e32 v27, v0
	v_mov_b32_e32 v28, v0
	v_mov_b32_e32 v29, v0
	v_mov_b32_e32 v30, v0
	v_mov_b32_e32 v31, v0
	v_mov_b32_e32 v40, v0
	v_mov_b32_e32 v41, v0
	v_mov_b32_e32 v42, v0
	v_mov_b32_e32 v43, v0
	v_mov_b32_e32 v44, v0
	v_mov_b32_e32 v45, v0
	v_mov_b32_e32 v46, v0
	v_mov_b32_e32 v47, v0
	v_mov_b32_e32 v64, v0
	v_mov_b32_e32 v65, v0
	v_mov_b32_e32 v66, v0
	v_mov_b32_e32 v67, v0
	v_mov_b32_e32 v68, v0
	v_mov_b32_e32 v69, v0
	v_mov_b32_e32 v70, v0
	v_mov_b32_e32 v71, v0
	v_mov_b32_e32 v80, v0
	v_mov_b32_e32 v81, v0
	v_mov_b32_e32 v82, v0
	v_mov_b32_e32 v83, v0
	v_mov_b32_e32 v84, v0
	v_mov_b32_e32 v85, v0
	v_mov_b32_e32 v86, v0
	v_mov_b32_e32 v87, v0
	v_mov_b32_e32 v96, v0
	v_mov_b32_e32 v97, v0
	v_mov_b32_e32 v98, v0
	v_mov_b32_e32 v99, v0
	v_mov_b32_e32 v100, v0
	v_mov_b32_e32 v101, v0
	v_mov_b32_e32 v102, v0
	v_mov_b32_e32 v103, v0
	v_mov_b32_e32 v112, v0
	v_mov_b32_e32 v113, v0
	v_mov_b32_e32 v114, v0
	v_mov_b32_e32 v115, v0
	v_mov_b32_e32 v116, v0
	v_mov_b32_e32 v117, v0
	v_mov_b32_e32 v118, v0
	v_mov_b32_e32 v119, v0
	v_mov_b32_e32 v48, v0
	v_mov_b32_e32 v49, v0
	v_mov_b32_e32 v50, v0
	v_mov_b32_e32 v51, v0
	v_mov_b32_e32 v52, v0
	v_mov_b32_e32 v53, v0
	v_mov_b32_e32 v54, v0
	v_mov_b32_e32 v55, v0
	v_mov_b32_e32 v88, v0
	v_mov_b32_e32 v89, v0
	v_mov_b32_e32 v90, v0
	v_mov_b32_e32 v91, v0
	v_mov_b32_e32 v92, v0
	v_mov_b32_e32 v93, v0
	v_mov_b32_e32 v94, v0
	v_mov_b32_e32 v95, v0
	v_mov_b32_e32 v104, v0
	v_mov_b32_e32 v105, v0
	v_mov_b32_e32 v106, v0
	v_mov_b32_e32 v107, v0
	v_mov_b32_e32 v108, v0
	v_mov_b32_e32 v109, v0
	v_mov_b32_e32 v110, v0
	v_mov_b32_e32 v111, v0
	v_mov_b32_e32 v120, v0
	v_mov_b32_e32 v121, v0
	v_mov_b32_e32 v122, v0
	v_mov_b32_e32 v123, v0
	v_mov_b32_e32 v124, v0
	v_mov_b32_e32 v125, v0
	v_mov_b32_e32 v126, v0
	v_mov_b32_e32 v127, v0
	v_mov_b32_e32 v72, v0
	v_mov_b32_e32 v73, v0
	v_mov_b32_e32 v74, v0
	v_mov_b32_e32 v75, v0
	v_mov_b32_e32 v76, v0
	v_mov_b32_e32 v77, v0
	v_mov_b32_e32 v78, v0
	v_mov_b32_e32 v79, v0
	v_readlane_b32 s98, v255, 17
	s_cmp_lg_u32 s98, 0
	s_cbranch_scc1 .Lsprio_0
	s_setprio 1

; DI int tid_of(int wave0) { int t = wave0 * 64 + lane_id(); asm volatile("" : "+v"(t)); return t; }
;     __host__ __device__ bool next(int i, Unit& u) const { return at((long)i * G + c, u); }
;     __host__ __device__ bool next(int i, Unit& u) const { if (i != 0 || c >= cnt) return false; u.pm = pm0 + c / nN; u.pn = c % nN; u.k0 = 0; u.nt = ntk; return true; }
; #define PG8_WAIT_V(n) asm volatile("s_waitcnt vmcnt(" #n ")" ::: "memory")
; #define PG8_BAR __builtin_amdgcn_s_barrier()
;     const int tid = tid_of(wave0), wid = wave0, lane = tid & 63, wr = wid >> 2, wc = wid & 3, fr = lane & 15, fq = lane >> 4;
;     const int K = g.K;
;     unsigned voffA[2], voffB[2];
; #pragma unroll
;     for (int i = 0; i < 2; ++i) { int R, C; stage_rc(tid * 16 + i * 8192, R, C); const int Rb = (R >> 5) * 64 + (Epi::PERM ? perm32(R & 31) : (R & 31));
;         voffA[i] = (unsigned)(R * K + C) * 2u; voffB[i] = (unsigned)(Rb * K + C) * 2u; }
;     const size_t kstep = (size_t)(BK * 2);
;     const size_t hstep = (size_t)HALF * K * 2;
;     const size_t tstep = 2 * hstep;
;     const size_t hstepB = (size_t)32 * K * 2;
;     const unsigned ldsw = (unsigned)wid * 1024u;
;     const int aoff = lds_byte(wr * 64 + fr, fq * 8), boff = lds_byte(wc * 32 + fr, fq * 8);
;     ...
;     Unit cur, nxt; int ui = 0;
;     if (!S.next(0, cur)) return;
;     f32x4 acc[2][2][4][2];
; #pragma unroll
;     for (int a = 0; a < 2; ++a)
; #pragma unroll
;         for (int b = 0; b < 2; ++b)
; #pragma unroll
;             for (int m = 0; m < 4; ++m)
; #pragma unroll
;                 for (int n = 0; n < 2; ++n) acc[a][b][m][n] = (f32x4){0.f, 0.f, 0.f, 0.f};
;     bf16x8 At[4][2], B0[2][2], B1[2][2];
;     const char* cA = (const char*)g.A + (size_t)cur.pm * tstep + (size_t)cur.k0 * (BK * 2); const char* cB = (const char*)g.Bt + (size_t)cur.pn * tstep + (size_t)cur.k0 * (BK * 2);
;     S.a_ready(cur);
;     if constexpr (SP2) {
;         PG8_STAGE(PG8_SB(0, 0), cB, voffB); PG8_STAGE(PG8_SB(0, 1), cB + hstepB, voffB); PG8_STAGEA(PG8_SA(0, 0), cA, voffA); PG8_STAGEA(PG8_SA(0, 1), cA + hstep, voffA);
;         if (wr == 1) PG8_BAR;
;         PG8_WAIT_V(2); PG8_BAR;
;         PG8_STAGE(PG8_SB(1, 0), cB + kstep, voffB); PG8_STAGEA(PG8_SA(1, 0), cA + kstep, voffA); PG8_STAGE(PG8_SB(1, 1), cB + hstepB + kstep, voffB);
;         PG8_WAIT_V(6); PG8_BAR;
.LBB0_443:
	v_and_b32_e32 v14, 15, v141
	v_or_b32_e32 v140, s72, v14
	v_lshlrev_b32_e32 v15, 6, v140
	v_and_b32_e32 v16, 48, v141
	s_movk_i32 s10, 0x3c0
	v_lshlrev_b32_e32 v17, 2, v140
	v_and_or_b32 v15, v15, s10, v16
	v_and_b32_e32 v17, 32, v17
	v_readlane_b32 s10, v255, 18
	v_lshl_or_b32 v14, v14, 6, v16
	v_lshlrev_b32_e32 v16, 2, v141
	v_bitop3_b32 v15, v15, s10, v17 bitop3:0xde
	v_and_b32_e32 v16, 32, v16
	v_readlane_b32 s10, v255, 19
	s_add_i32 m0, s1, 0x18000
	s_waitcnt vmcnt(2)
	s_barrier
	v_bitop3_b32 v14, v14, s10, v16 bitop3:0xde
	s_mov_b64 s[10:11], 0x80
	v_lshl_add_u64 v[6:7], v[6:7], 0, s[10:11]
	global_load_lds_dwordx4 v[6:7], off
	v_lshl_add_u64 v[4:5], v[4:5], 0, s[10:11]
	s_add_i32 m0, s1, 0x1a000
	s_add_i32 s20, s1, 0x8000
	s_add_i32 s21, s1, 0xa000
	global_load_lds_dwordx4 v[4:5], off
	v_lshl_add_u64 v[0:1], v[0:1], 0, s[10:11]
	s_mov_b32 m0, s20
	s_add_u32 s14, s6, 0x10080
	global_load_lds_dwordx4 v[0:1], off
	v_lshl_add_u64 v[0:1], v[2:3], 0, s[10:11]
	s_mov_b32 m0, s21
	s_addc_u32 s15, s7, 0
	global_load_lds_dwordx4 v[0:1], off
	s_add_i32 m0, s1, 0x1c000
	v_lshl_add_u64 v[0:1], s[14:15], 0, v[132:133]
	global_load_lds_dwordx4 v[0:1], off
	v_lshl_add_u64 v[0:1], s[14:15], 0, v[128:129]
	s_add_i32 m0, s1, 0x1e000
	s_ashr_i32 s13, s12, 31
	global_load_lds_dwordx4 v[0:1], off
	v_lshlrev_b32_e32 v0, 14, v12
	v_and_b32_e32 v0, 0xffff8000, v0
	s_lshl_b64 s[12:13], s[12:13], 19
	v_lshl_add_u32 v0, v11, 11, v0
	v_and_b32_e32 v1, 1, v12
	v_lshl_or_b32 v0, v1, 6, v0
	s_add_u32 s12, s68, s12
	v_lshl_add_u32 v0, v13, 1, v0
	v_mov_b32_e32 v1, v133
	s_addc_u32 s13, s69, s13
	v_lshl_add_u64 v[136:137], s[12:13], 0, v[0:1]
	v_lshlrev_b32_e32 v0, 14, v8
	v_and_b32_e32 v0, 0xffff8000, v0
	v_lshl_add_u32 v0, v9, 11, v0
	v_and_b32_e32 v1, 1, v8
	s_waitcnt vmcnt(6)
	v_lshl_or_b32 v0, v1, 6, v0
	s_add_i32 s25, 0, 0x10000
	s_add_i32 s27, 0, 0x14000
	s_add_i32 s29, 0, 0x18000
	s_add_i32 s31, 0, 0x1c000
	v_lshl_add_u32 v0, v10, 1, v0
	v_mov_b32_e32 v1, v133
	v_add_u32_e32 v142, s25, v14
	v_add_u32_e32 v143, s27, v14
	s_add_i32 s25, s25, s67
	s_add_i32 s27, s27, s67
	v_add_u32_e32 v145, s29, v14
	v_add_u32_e32 v146, s31, v14
	s_add_i32 s29, s29, s67
	s_add_i32 s31, s31, s67
	v_lshl_add_u64 v[138:139], s[12:13], 0, v[0:1]
	s_mov_b32 s22, -2
	s_mov_b64 s[12:13], 0xda40080
	v_add_u32_e32 v144, 0, v15
	s_add_i32 s23, s1, 0xc000
	s_add_i32 s24, s1, 0xe000
	s_add_i32 s26, s25, 0x2000
	s_add_i32 s28, s27, 0x2000
	s_add_i32 s30, s29, 0x2000
	s_add_i32 s34, s31, 0x2000
	v_mov_b32_e32 v0, v133
	v_mov_b32_e32 v2, v133
	v_mov_b32_e32 v3, v133
	v_mov_b32_e32 v4, v133
	v_mov_b32_e32 v5, v133
	v_mov_b32_e32 v6, v133
	v_mov_b32_e32 v7, v133
	v_mov_b32_e32 v16, v133
	v_mov_b32_e32 v17, v133
	v_mov_b32_e32 v18, v133
	v_mov_b32_e32 v19, v133
	v_mov_b32_e32 v20, v133
	v_mov_b32_e32 v21, v133
	v_mov_b32_e32 v22, v133
	v_mov_b32_e32 v23, v133
	v_mov_b32_e32 v32, v133
	v_mov_b32_e32 v33, v133
	v_mov_b32_e32 v34, v133
	v_mov_b32_e32 v35, v133
	v_mov_b32_e32 v36, v133
	v_mov_b32_e32 v37, v133
	v_mov_b32_e32 v38, v133
	v_mov_b32_e32 v39, v133
	v_mov_b32_e32 v48, v133
	v_mov_b32_e32 v49, v133
	v_mov_b32_e32 v50, v133
	v_mov_b32_e32 v51, v133
	v_mov_b32_e32 v52, v133
	v_mov_b32_e32 v53, v133
	v_mov_b32_e32 v54, v133
	v_mov_b32_e32 v55, v133
	v_mov_b32_e32 v8, v133
	v_mov_b32_e32 v9, v133
	v_mov_b32_e32 v10, v133
	v_mov_b32_e32 v11, v133
	v_mov_b32_e32 v12, v133
	v_mov_b32_e32 v13, v133
	v_mov_b32_e32 v14, v133
	v_mov_b32_e32 v15, v133
	v_mov_b32_e32 v24, v133
	v_mov_b32_e32 v25, v133
	v_mov_b32_e32 v26, v133
	v_mov_b32_e32 v27, v133
	v_mov_b32_e32 v28, v133
	v_mov_b32_e32 v29, v133
	v_mov_b32_e32 v30, v133
	v_mov_b32_e32 v31, v133
	v_mov_b32_e32 v40, v133
	v_mov_b32_e32 v41, v133
	v_mov_b32_e32 v42, v133
	v_mov_b32_e32 v43, v133
	v_mov_b32_e32 v44, v133
	v_mov_b32_e32 v45, v133
	v_mov_b32_e32 v46, v133
	v_mov_b32_e32 v47, v133
	v_mov_b32_e32 v56, v133
	v_mov_b32_e32 v57, v133
	v_mov_b32_e32 v58, v133
	v_mov_b32_e32 v59, v133
	v_mov_b32_e32 v60, v133
	v_mov_b32_e32 v61, v133
	v_mov_b32_e32 v62, v133
	v_mov_b32_e32 v63, v133
	v_mov_b32_e32 v64, v133
	v_mov_b32_e32 v65, v133
	v_mov_b32_e32 v66, v133
	v_mov_b32_e32 v67, v133
	v_mov_b32_e32 v68, v133
	v_mov_b32_e32 v69, v133
	v_mov_b32_e32 v70, v133
	v_mov_b32_e32 v71, v133
	v_mov_b32_e32 v80, v133
	v_mov_b32_e32 v81, v133
	v_mov_b32_e32 v82, v133
	v_mov_b32_e32 v83, v133
	v_mov_b32_e32 v84, v133
	v_mov_b32_e32 v85, v133
	v_mov_b32_e32 v86, v133
	v_mov_b32_e32 v87, v133
	v_mov_b32_e32 v96, v133
	v_mov_b32_e32 v97, v133
	v_mov_b32_e32 v98, v133
	v_mov_b32_e32 v99, v133
	v_mov_b32_e32 v100, v133
	v_mov_b32_e32 v101, v133
	v_mov_b32_e32 v102, v133
	v_mov_b32_e32 v103, v133
	v_mov_b32_e32 v112, v133
	v_mov_b32_e32 v113, v133
	v_mov_b32_e32 v114, v133
	v_mov_b32_e32 v115, v133
	v_mov_b32_e32 v116, v133
	v_mov_b32_e32 v117, v133
	v_mov_b32_e32 v118, v133
	v_mov_b32_e32 v119, v133
	v_mov_b32_e32 v72, v133
	v_mov_b32_e32 v73, v133
	v_mov_b32_e32 v74, v133
	v_mov_b32_e32 v75, v133
	v_mov_b32_e32 v76, v133
	v_mov_b32_e32 v77, v133
	v_mov_b32_e32 v78, v133
	v_mov_b32_e32 v79, v133
	v_mov_b32_e32 v88, v133
	v_mov_b32_e32 v89, v133
	v_mov_b32_e32 v90, v133
	v_mov_b32_e32 v91, v133
	v_mov_b32_e32 v92, v133
	v_mov_b32_e32 v93, v133
	v_mov_b32_e32 v94, v133
	v_mov_b32_e32 v95, v133
	v_mov_b32_e32 v104, v133
	v_mov_b32_e32 v105, v133
	v_mov_b32_e32 v106, v133
	v_mov_b32_e32 v107, v133
	v_mov_b32_e32 v108, v133
	v_mov_b32_e32 v109, v133
	v_mov_b32_e32 v110, v133
	v_mov_b32_e32 v111, v133
	v_mov_b32_e32 v120, v133
	v_mov_b32_e32 v121, v133
	v_mov_b32_e32 v122, v133
	v_mov_b32_e32 v123, v133
	v_mov_b32_e32 v124, v133
	v_mov_b32_e32 v125, v133
	v_mov_b32_e32 v126, v133
	v_mov_b32_e32 v127, v133
	s_barrier
	v_readlane_b32 s98, v255, 17
	s_cmp_lg_u32 s98, 0
	s_cbranch_scc1 .Lsprio_1
	s_setprio 1

; DI int tid_of(int wave0) { int t = wave0 * 64 + lane_id(); asm volatile("" : "+v"(t)); return t; }
;     __host__ __device__ bool next(int i, Unit& u) const { return at((long)i * G + c, u); }
;     __host__ __device__ bool next(int i, Unit& u) const { if (i != 0 || c >= cnt) return false; u.pm = pm0 + c / nN; u.pn = c % nN; u.k0 = 0; u.nt = ntk; return true; }
; #define PG8_WAIT_V(n) asm volatile("s_waitcnt vmcnt(" #n ")" ::: "memory")
; #define PG8_BAR __builtin_amdgcn_s_barrier()
;     const int tid = tid_of(wave0), wid = wave0, lane = tid & 63, wr = wid >> 2, wc = wid & 3, fr = lane & 15, fq = lane >> 4;
;     const int K = g.K;
;     unsigned voffA[2], voffB[2];
; #pragma unroll
;     for (int i = 0; i < 2; ++i) { int R, C; stage_rc(tid * 16 + i * 8192, R, C); const int Rb = (R >> 5) * 64 + (Epi::PERM ? perm32(R & 31) : (R & 31));
;         voffA[i] = (unsigned)(R * K + C) * 2u; voffB[i] = (unsigned)(Rb * K + C) * 2u; }
;     const size_t kstep = (size_t)(BK * 2);
;     const size_t hstep = (size_t)HALF * K * 2;
;     const size_t tstep = 2 * hstep;
;     const size_t hstepB = (size_t)32 * K * 2;
;     const unsigned ldsw = (unsigned)wid * 1024u;
;     const int aoff = lds_byte(wr * 64 + fr, fq * 8), boff = lds_byte(wc * 32 + fr, fq * 8);
;     ...
;     Unit cur, nxt; int ui = 0;
;     if (!S.next(0, cur)) return;
;     f32x4 acc[2][2][4][2];
; #pragma unroll
;     for (int a = 0; a < 2; ++a)
; #pragma unroll
;         for (int b = 0; b < 2; ++b)
; #pragma unroll
;             for (int m = 0; m < 4; ++m)
; #pragma unroll
;                 for (int n = 0; n < 2; ++n) acc[a][b][m][n] = (f32x4){0.f, 0.f, 0.f, 0.f};
;     bf16x8 At[4][2], B0[2][2], B1[2][2];
;     const char* cA = (const char*)g.A + (size_t)cur.pm * tstep + (size_t)cur.k0 * (BK * 2); const char* cB = (const char*)g.Bt + (size_t)cur.pn * tstep + (size_t)cur.k0 * (BK * 2);
;     S.a_ready(cur);
;     if constexpr (SP2) {
;         PG8_STAGE(PG8_SB(0, 0), cB, voffB); PG8_STAGE(PG8_SB(0, 1), cB + hstepB, voffB); PG8_STAGEA(PG8_SA(0, 0), cA, voffA); PG8_STAGEA(PG8_SA(0, 1), cA + hstep, voffA);
;         if (wr == 1) PG8_BAR;
;         PG8_WAIT_V(2); PG8_BAR;
;         PG8_STAGE(PG8_SB(1, 0), cB + kstep, voffB); PG8_STAGEA(PG8_SA(1, 0), cA + kstep, voffA); PG8_STAGE(PG8_SB(1, 1), cB + hstepB + kstep, voffB);
;         PG8_WAIT_V(6); PG8_BAR;
.LBB0_757:
	v_and_b32_e32 v15, 15, v11
	v_lshrrev_b32_e32 v16, 1, v11
	v_or_b32_e32 v129, s72, v15
	v_and_b32_e32 v16, 24, v16
	v_lshlrev_b32_e32 v17, 6, v129
	v_lshlrev_b32_e32 v128, 1, v16
	s_movk_i32 s10, 0x3c0
	v_and_or_b32 v16, v17, s10, v128
	v_lshlrev_b32_e32 v17, 2, v129
	v_and_b32_e32 v17, 32, v17
	v_readlane_b32 s10, v255, 18
	v_lshlrev_b32_e32 v11, 2, v11
	v_lshl_or_b32 v15, v15, 6, v128
	v_bitop3_b32 v16, v16, s10, v17 bitop3:0xde
	v_and_b32_e32 v11, 32, v11
	v_readlane_b32 s10, v255, 19
	s_add_i32 m0, s1, 0x18000
	s_waitcnt vmcnt(2)
	s_barrier
	v_bitop3_b32 v11, v15, s10, v11 bitop3:0xde
	s_mov_b64 s[10:11], 0x80
	v_lshl_add_u64 v[6:7], v[6:7], 0, s[10:11]
	global_load_lds_dwordx4 v[6:7], off
	v_lshl_add_u64 v[4:5], v[4:5], 0, s[10:11]
	s_add_i32 m0, s1, 0x1a000
	s_add_i32 s20, s1, 0x8000
	s_add_i32 s21, s1, 0xa000
	global_load_lds_dwordx4 v[4:5], off
	v_lshl_add_u64 v[0:1], v[0:1], 0, s[10:11]
	s_mov_b32 m0, s20
	s_add_u32 s14, s6, 0x10080
	global_load_lds_dwordx4 v[0:1], off
	v_lshl_add_u64 v[0:1], v[2:3], 0, s[10:11]
	s_mov_b32 m0, s21
	s_addc_u32 s15, s7, 0
	global_load_lds_dwordx4 v[0:1], off
	s_add_i32 m0, s1, 0x1c000
	v_lshl_add_u64 v[0:1], s[14:15], 0, v[134:135]
	global_load_lds_dwordx4 v[0:1], off
	v_lshl_add_u64 v[0:1], s[14:15], 0, v[130:131]
	s_add_i32 m0, s1, 0x1e000
	s_ashr_i32 s13, s12, 31
	global_load_lds_dwordx4 v[0:1], off
	v_lshlrev_b32_e32 v0, 14, v13
	v_and_b32_e32 v0, 0xffff8000, v0
	s_lshl_b64 s[12:13], s[12:13], 19
	v_lshl_add_u32 v0, v12, 11, v0
	v_and_b32_e32 v1, 1, v13
	v_lshl_or_b32 v0, v1, 6, v0
	s_add_u32 s12, s68, s12
	v_lshl_add_u32 v0, v14, 1, v0
	v_mov_b32_e32 v1, v135
	s_addc_u32 s13, s69, s13
	v_lshl_add_u64 v[138:139], s[12:13], 0, v[0:1]
	v_lshlrev_b32_e32 v0, 14, v8
	v_and_b32_e32 v0, 0xffff8000, v0
	v_lshl_add_u32 v0, v9, 11, v0
	v_and_b32_e32 v1, 1, v8
	s_waitcnt vmcnt(6)
	v_lshl_or_b32 v0, v1, 6, v0
	s_add_i32 s25, 0, 0x10000
	s_add_i32 s27, 0, 0x14000
	s_add_i32 s29, 0, 0x18000
	s_add_i32 s31, 0, 0x1c000
	v_lshl_add_u32 v0, v10, 1, v0
	v_mov_b32_e32 v1, v135
	v_add_u32_e32 v142, s25, v11
	v_add_u32_e32 v143, s27, v11
	s_add_i32 s25, s25, s67
	s_add_i32 s27, s27, s67
	v_add_u32_e32 v145, s29, v11
	v_add_u32_e32 v146, s31, v11
	s_add_i32 s29, s29, s67
	s_add_i32 s31, s31, s67
	v_lshl_add_u64 v[140:141], s[12:13], 0, v[0:1]
	s_mov_b32 s22, -2
	s_mov_b64 s[12:13], 0xfc40080
	v_add_u32_e32 v144, 0, v16
	s_add_i32 s23, s1, 0xc000
	s_add_i32 s24, s1, 0xe000
	s_add_i32 s26, s25, 0x2000
	s_add_i32 s28, s27, 0x2000
	s_add_i32 s30, s29, 0x2000
	s_add_i32 s34, s31, 0x2000
	v_mov_b32_e32 v0, v135
	v_mov_b32_e32 v2, v135
	v_mov_b32_e32 v3, v135
	v_mov_b32_e32 v4, v135
	v_mov_b32_e32 v5, v135
	v_mov_b32_e32 v6, v135
	v_mov_b32_e32 v7, v135
	v_mov_b32_e32 v16, v135
	v_mov_b32_e32 v17, v135
	v_mov_b32_e32 v18, v135
	v_mov_b32_e32 v19, v135
	v_mov_b32_e32 v20, v135
	v_mov_b32_e32 v21, v135
	v_mov_b32_e32 v22, v135
	v_mov_b32_e32 v23, v135
	v_mov_b32_e32 v32, v135
	v_mov_b32_e32 v33, v135
	v_mov_b32_e32 v34, v135
	v_mov_b32_e32 v35, v135
	v_mov_b32_e32 v36, v135
	v_mov_b32_e32 v37, v135
	v_mov_b32_e32 v38, v135
	v_mov_b32_e32 v39, v135
	v_mov_b32_e32 v48, v135
	v_mov_b32_e32 v49, v135
	v_mov_b32_e32 v50, v135
	v_mov_b32_e32 v51, v135
	v_mov_b32_e32 v52, v135
	v_mov_b32_e32 v53, v135
	v_mov_b32_e32 v54, v135
	v_mov_b32_e32 v55, v135
	v_mov_b32_e32 v8, v135
	v_mov_b32_e32 v9, v135
	v_mov_b32_e32 v10, v135
	v_mov_b32_e32 v11, v135
	v_mov_b32_e32 v12, v135
	v_mov_b32_e32 v13, v135
	v_mov_b32_e32 v14, v135
	v_mov_b32_e32 v15, v135
	v_mov_b32_e32 v24, v135
	v_mov_b32_e32 v25, v135
	v_mov_b32_e32 v26, v135
	v_mov_b32_e32 v27, v135
	v_mov_b32_e32 v28, v135
	v_mov_b32_e32 v29, v135
	v_mov_b32_e32 v30, v135
	v_mov_b32_e32 v31, v135
	v_mov_b32_e32 v40, v135
	v_mov_b32_e32 v41, v135
	v_mov_b32_e32 v42, v135
	v_mov_b32_e32 v43, v135
	v_mov_b32_e32 v44, v135
	v_mov_b32_e32 v45, v135
	v_mov_b32_e32 v46, v135
	v_mov_b32_e32 v47, v135
	v_mov_b32_e32 v56, v135
	v_mov_b32_e32 v57, v135
	v_mov_b32_e32 v58, v135
	v_mov_b32_e32 v59, v135
	v_mov_b32_e32 v60, v135
	v_mov_b32_e32 v61, v135
	v_mov_b32_e32 v62, v135
	v_mov_b32_e32 v63, v135
	v_mov_b32_e32 v64, v135
	v_mov_b32_e32 v65, v135
	v_mov_b32_e32 v66, v135
	v_mov_b32_e32 v67, v135
	v_mov_b32_e32 v68, v135
	v_mov_b32_e32 v69, v135
	v_mov_b32_e32 v70, v135
	v_mov_b32_e32 v71, v135
	v_mov_b32_e32 v80, v135
	v_mov_b32_e32 v81, v135
	v_mov_b32_e32 v82, v135
	v_mov_b32_e32 v83, v135
	v_mov_b32_e32 v84, v135
	v_mov_b32_e32 v85, v135
	v_mov_b32_e32 v86, v135
	v_mov_b32_e32 v87, v135
	v_mov_b32_e32 v96, v135
	v_mov_b32_e32 v97, v135
	v_mov_b32_e32 v98, v135
	v_mov_b32_e32 v99, v135
	v_mov_b32_e32 v100, v135
	v_mov_b32_e32 v101, v135
	v_mov_b32_e32 v102, v135
	v_mov_b32_e32 v103, v135
	v_mov_b32_e32 v112, v135
	v_mov_b32_e32 v113, v135
	v_mov_b32_e32 v114, v135
	v_mov_b32_e32 v115, v135
	v_mov_b32_e32 v116, v135
	v_mov_b32_e32 v117, v135
	v_mov_b32_e32 v118, v135
	v_mov_b32_e32 v119, v135
	v_mov_b32_e32 v72, v135
	v_mov_b32_e32 v73, v135
	v_mov_b32_e32 v74, v135
	v_mov_b32_e32 v75, v135
	v_mov_b32_e32 v76, v135
	v_mov_b32_e32 v77, v135
	v_mov_b32_e32 v78, v135
	v_mov_b32_e32 v79, v135
	v_mov_b32_e32 v88, v135
	v_mov_b32_e32 v89, v135
	v_mov_b32_e32 v90, v135
	v_mov_b32_e32 v91, v135
	v_mov_b32_e32 v92, v135
	v_mov_b32_e32 v93, v135
	v_mov_b32_e32 v94, v135
	v_mov_b32_e32 v95, v135
	v_mov_b32_e32 v104, v135
	v_mov_b32_e32 v105, v135
	v_mov_b32_e32 v106, v135
	v_mov_b32_e32 v107, v135
	v_mov_b32_e32 v108, v135
	v_mov_b32_e32 v109, v135
	v_mov_b32_e32 v110, v135
	v_mov_b32_e32 v111, v135
	v_mov_b32_e32 v120, v135
	v_mov_b32_e32 v121, v135
	v_mov_b32_e32 v122, v135
	v_mov_b32_e32 v123, v135
	v_mov_b32_e32 v124, v135
	v_mov_b32_e32 v125, v135
	v_mov_b32_e32 v126, v135
	v_mov_b32_e32 v127, v135
	s_barrier
	v_readlane_b32 s98, v255, 17
	s_cmp_lg_u32 s98, 0
	s_cbranch_scc1 .Lsprio_2
	s_setprio 1

;     __host__ __device__ bool next(int i, Unit& u) const { return at((long)i * G + c, u); }
;     __host__ __device__ bool next(int i, Unit& u) const { if (i != 0 || c >= cnt) return false; u.pm = pm0 + c / nN; u.pn = c % nN; u.k0 = 0; u.nt = ntk; return true; }
;     ...
;         const bool has_next = S.next(ui + 1, nxt);
;         const char* nA = has_next ? (const char*)g.A + (size_t)nxt.pm * tstep + (size_t)nxt.k0 * (BK * 2) : cA; const char* nB = has_next ? (const char*)g.Bt + (size_t)nxt.pn * tstep + (size_t)nxt.k0 * (BK * 2) : cB;
;     ...
; #pragma unroll
;         for (int a = 0; a < 2; ++a)
; #pragma unroll
;             for (int b = 0; b < 2; ++b)
; #pragma unroll
;                 for (int m = 0; m < 4; ++m)
; #pragma unroll
;                     for (int n = 0; n < 2; ++n) acc[a][b][m][n] = (f32x4){0.f, 0.f, 0.f, 0.f};
.LBB0_853:
	s_ashr_i32 s25, s24, 31
	s_lshl_b64 s[26:27], s[24:25], 19
	s_add_u32 s26, s6, s26
	s_addc_u32 s27, s7, s27
	s_and_b64 s[28:29], s[4:5], exec
	s_cselect_b32 s15, s27, s35
	s_cselect_b32 s25, s26, s34
	s_ashr_i32 s23, s22, 31
	s_lshl_b64 s[28:29], s[22:23], 19
	s_add_u32 s28, s3, s28
	s_addc_u32 s29, s42, s29
	s_and_b64 s[38:39], s[4:5], exec
	s_cselect_b32 s23, s29, s37
	s_cselect_b32 s31, s28, s36
	s_add_u32 s34, s34, 0x40080
	s_addc_u32 s35, s35, 0
	s_add_u32 s56, s36, 0x100
	v_mov_b32_e32 v0, 0
	s_addc_u32 s57, s37, 0
	s_mov_b32 s58, -2
	s_waitcnt lgkmcnt(0)
	v_mov_b32_e32 v1, v0
	v_mov_b32_e32 v2, v0
	v_mov_b32_e32 v3, v0
	v_mov_b32_e32 v4, v0
	v_mov_b32_e32 v5, v0
	v_mov_b32_e32 v6, v0
	v_mov_b32_e32 v7, v0
	v_mov_b32_e32 v16, v0
	v_mov_b32_e32 v17, v0
	v_mov_b32_e32 v18, v0
	v_mov_b32_e32 v19, v0
	v_mov_b32_e32 v20, v0
	v_mov_b32_e32 v21, v0
	v_mov_b32_e32 v22, v0
	v_mov_b32_e32 v23, v0
	v_mov_b32_e32 v32, v0
	v_mov_b32_e32 v33, v0
	v_mov_b32_e32 v34, v0
	v_mov_b32_e32 v35, v0
	v_mov_b32_e32 v36, v0
	v_mov_b32_e32 v37, v0
	v_mov_b32_e32 v38, v0
	v_mov_b32_e32 v39, v0
	v_mov_b32_e32 v48, v0
	v_mov_b32_e32 v49, v0
	v_mov_b32_e32 v50, v0
	v_mov_b32_e32 v51, v0
	v_mov_b32_e32 v52, v0
	v_mov_b32_e32 v53, v0
	v_mov_b32_e32 v54, v0
	v_mov_b32_e32 v55, v0
	v_mov_b32_e32 v8, v0
	v_mov_b32_e32 v9, v0
	v_mov_b32_e32 v10, v0
	v_mov_b32_e32 v11, v0
	v_mov_b32_e32 v12, v0
	v_mov_b32_e32 v13, v0
	v_mov_b32_e32 v14, v0
	v_mov_b32_e32 v15, v0
	v_mov_b32_e32 v24, v0
	v_mov_b32_e32 v25, v0
	v_mov_b32_e32 v26, v0
	v_mov_b32_e32 v27, v0
	v_mov_b32_e32 v28, v0
	v_mov_b32_e32 v29, v0
	v_mov_b32_e32 v30, v0
	v_mov_b32_e32 v31, v0
	v_mov_b32_e32 v40, v0
	v_mov_b32_e32 v41, v0
	v_mov_b32_e32 v42, v0
	v_mov_b32_e32 v43, v0
	v_mov_b32_e32 v44, v0
	v_mov_b32_e32 v45, v0
	v_mov_b32_e32 v46, v0
	v_mov_b32_e32 v47, v0
	v_mov_b32_e32 v56, v0
	v_mov_b32_e32 v57, v0
	v_mov_b32_e32 v58, v0
	v_mov_b32_e32 v59, v0
	v_mov_b32_e32 v60, v0
	v_mov_b32_e32 v61, v0
	v_mov_b32_e32 v62, v0
	v_mov_b32_e32 v63, v0
	v_mov_b32_e32 v64, v0
	v_mov_b32_e32 v65, v0
	v_mov_b32_e32 v66, v0
	v_mov_b32_e32 v67, v0
	v_mov_b32_e32 v68, v0
	v_mov_b32_e32 v69, v0
	v_mov_b32_e32 v70, v0
	v_mov_b32_e32 v71, v0
	v_mov_b32_e32 v80, v0
	v_mov_b32_e32 v81, v0
	v_mov_b32_e32 v82, v0
	v_mov_b32_e32 v83, v0
	v_mov_b32_e32 v84, v0
	v_mov_b32_e32 v85, v0
	v_mov_b32_e32 v86, v0
	v_mov_b32_e32 v87, v0
	v_mov_b32_e32 v96, v0
	v_mov_b32_e32 v97, v0
	v_mov_b32_e32 v98, v0
	v_mov_b32_e32 v99, v0
	v_mov_b32_e32 v100, v0
	v_mov_b32_e32 v101, v0
	v_mov_b32_e32 v102, v0
	v_mov_b32_e32 v103, v0
	v_mov_b32_e32 v112, v0
	v_mov_b32_e32 v113, v0
	v_mov_b32_e32 v114, v0
	v_mov_b32_e32 v115, v0
	v_mov_b32_e32 v116, v0
	v_mov_b32_e32 v117, v0
	v_mov_b32_e32 v118, v0
	v_mov_b32_e32 v119, v0
	v_mov_b32_e32 v72, v0
	v_mov_b32_e32 v73, v0
	v_mov_b32_e32 v74, v0
	v_mov_b32_e32 v75, v0
	v_mov_b32_e32 v76, v0
	v_mov_b32_e32 v77, v0
	v_mov_b32_e32 v78, v0
	v_mov_b32_e32 v79, v0
	v_mov_b32_e32 v88, v0
	v_mov_b32_e32 v89, v0
	v_mov_b32_e32 v90, v0
	v_mov_b32_e32 v91, v0
	v_mov_b32_e32 v92, v0
	v_mov_b32_e32 v93, v0
	v_mov_b32_e32 v94, v0
	v_mov_b32_e32 v95, v0
	v_mov_b32_e32 v104, v0
	v_mov_b32_e32 v105, v0
	v_mov_b32_e32 v106, v0
	v_mov_b32_e32 v107, v0
	v_mov_b32_e32 v108, v0
	v_mov_b32_e32 v109, v0
	v_mov_b32_e32 v110, v0
	v_mov_b32_e32 v111, v0
	v_mov_b32_e32 v120, v0
	v_mov_b32_e32 v121, v0
	v_mov_b32_e32 v122, v0
	v_mov_b32_e32 v123, v0
	v_mov_b32_e32 v124, v0
	v_mov_b32_e32 v125, v0
	v_mov_b32_e32 v126, v0
	v_mov_b32_e32 v127, v0
	v_readlane_b32 s98, v255, 17
	s_cmp_lg_u32 s98, 0
	s_cbranch_scc1 .Lsprio_3
	s_setprio 1

;     __host__ __device__ bool next(int i, Unit& u) const { return at((long)i * G + c, u); }
;     __host__ __device__ bool next(int i, Unit& u) const { if (i != 0 || c >= cnt) return false; u.pm = pm0 + c / nN; u.pn = c % nN; u.k0 = 0; u.nt = ntk; return true; }
;     ...
;         const bool has_next = S.next(ui + 1, nxt);
;         const char* nA = has_next ? (const char*)g.A + (size_t)nxt.pm * tstep + (size_t)nxt.k0 * (BK * 2) : cA; const char* nB = has_next ? (const char*)g.Bt + (size_t)nxt.pn * tstep + (size_t)nxt.k0 * (BK * 2) : cB;
;         const int nt = cur.nt;
;         for (int t = 0; t < nt; t += 2) {
;             const bool last = (t == nt - 2);
;             const char* a1 = cA + (size_t)(t + 1) * kstep;
;             const char* a2 = last ? nA : cA + (size_t)(t + 2) * kstep; const char* b2 = last ? nB : cB + (size_t)(t + 2) * kstep;
;             const char* a3 = a2 + kstep; const char* b3 = b2 + kstep;
.LBB0_887:
	s_add_u32 s54, s36, 0x100
	s_addc_u32 s55, s37, 0
	s_ashr_i32 s27, s26, 31
	s_lshl_b64 s[28:29], s[26:27], 19
	s_add_u32 s28, s6, s28
	s_addc_u32 s29, s7, s29
	s_and_b64 s[30:31], s[4:5], exec
	s_cselect_b32 s27, s29, s35
	s_cselect_b32 s56, s28, s34
	s_ashr_i32 s25, s24, 31
	s_lshl_b64 s[30:31], s[24:25], 19
	s_add_u32 s30, s3, s30
	s_addc_u32 s31, s42, s31
	s_and_b64 s[38:39], s[4:5], exec
	s_cselect_b32 s25, s31, s37
	s_cselect_b32 s57, s30, s36
	v_lshl_add_u64 v[142:143], s[34:35], 0, v[136:137]
	v_lshl_add_u64 v[144:145], s[34:35], 0, v[138:139]
	s_mov_b32 s58, -2
	s_mov_b64 s[36:37], 0
	v_readlane_b32 s98, v255, 17
	s_cmp_lg_u32 s98, 0
	s_cbranch_scc1 .Lsprio_4
	s_setprio 1

;     __host__ __device__ bool next(int i, Unit& u) const { return at((long)i * G + c, u); }
;     __host__ __device__ bool next(int i, Unit& u) const { if (i != 0 || c >= cnt) return false; u.pm = pm0 + c / nN; u.pn = c % nN; u.k0 = 0; u.nt = ntk; return true; }
;     ...
;         const bool has_next = S.next(ui + 1, nxt);
;         const char* nA = has_next ? (const char*)g.A + (size_t)nxt.pm * tstep + (size_t)nxt.k0 * (BK * 2) : cA; const char* nB = has_next ? (const char*)g.Bt + (size_t)nxt.pn * tstep + (size_t)nxt.k0 * (BK * 2) : cB;
;     ...
; #pragma unroll
;         for (int a = 0; a < 2; ++a)
; #pragma unroll
;             for (int b = 0; b < 2; ++b)
; #pragma unroll
;                 for (int m = 0; m < 4; ++m)
; #pragma unroll
;                     for (int n = 0; n < 2; ++n) acc[a][b][m][n] = (f32x4){0.f, 0.f, 0.f, 0.f};
.LBB0_976:
	s_ashr_i32 s27, s26, 31
	s_lshl_b64 s[28:29], s[26:27], 19
	s_add_u32 s28, s8, s28
	s_addc_u32 s29, s9, s29
	s_and_b64 s[30:31], s[0:1], exec
	s_cselect_b32 s27, s29, s39
	s_cselect_b32 s35, s28, s38
	s_ashr_i32 s25, s24, 31
	s_lshl_b64 s[30:31], s[24:25], 19
	s_add_u32 s30, s3, s30
	s_addc_u32 s31, s21, s31
	s_and_b64 s[42:43], s[0:1], exec
	s_cselect_b32 s25, s31, s41
	s_cselect_b32 s58, s30, s40
	s_add_u32 s38, s38, 0x40080
	s_addc_u32 s39, s39, 0
	s_add_u32 s59, s40, 0x100
	v_mov_b32_e32 v0, 0
	s_addc_u32 s70, s41, 0
	s_mov_b32 s71, -2
	v_mov_b32_e32 v1, v0
	v_mov_b32_e32 v2, v0
	v_mov_b32_e32 v3, v0
	v_mov_b32_e32 v4, v0
	v_mov_b32_e32 v5, v0
	v_mov_b32_e32 v6, v0
	v_mov_b32_e32 v7, v0
	v_mov_b32_e32 v16, v0
	v_mov_b32_e32 v17, v0
	v_mov_b32_e32 v18, v0
	v_mov_b32_e32 v19, v0
	v_mov_b32_e32 v20, v0
	v_mov_b32_e32 v21, v0
	v_mov_b32_e32 v22, v0
	v_mov_b32_e32 v23, v0
	v_mov_b32_e32 v32, v0
	v_mov_b32_e32 v33, v0
	v_mov_b32_e32 v34, v0
	v_mov_b32_e32 v35, v0
	v_mov_b32_e32 v36, v0
	v_mov_b32_e32 v37, v0
	v_mov_b32_e32 v38, v0
	v_mov_b32_e32 v39, v0
	v_mov_b32_e32 v48, v0
	v_mov_b32_e32 v49, v0
	v_mov_b32_e32 v50, v0
	v_mov_b32_e32 v51, v0
	v_mov_b32_e32 v52, v0
	v_mov_b32_e32 v53, v0
	v_mov_b32_e32 v54, v0
	v_mov_b32_e32 v55, v0
	v_mov_b32_e32 v8, v0
	v_mov_b32_e32 v9, v0
	v_mov_b32_e32 v10, v0
	v_mov_b32_e32 v11, v0
	v_mov_b32_e32 v12, v0
	v_mov_b32_e32 v13, v0
	v_mov_b32_e32 v14, v0
	v_mov_b32_e32 v15, v0
	v_mov_b32_e32 v24, v0
	v_mov_b32_e32 v25, v0
	v_mov_b32_e32 v26, v0
	v_mov_b32_e32 v27, v0
	v_mov_b32_e32 v28, v0
	v_mov_b32_e32 v29, v0
	v_mov_b32_e32 v30, v0
	v_mov_b32_e32 v31, v0
	v_mov_b32_e32 v40, v0
	v_mov_b32_e32 v41, v0
	v_mov_b32_e32 v42, v0
	v_mov_b32_e32 v43, v0
	v_mov_b32_e32 v44, v0
	v_mov_b32_e32 v45, v0
	v_mov_b32_e32 v46, v0
	v_mov_b32_e32 v47, v0
	v_mov_b32_e32 v56, v0
	v_mov_b32_e32 v57, v0
	v_mov_b32_e32 v58, v0
	v_mov_b32_e32 v59, v0
	v_mov_b32_e32 v60, v0
	v_mov_b32_e32 v61, v0
	v_mov_b32_e32 v62, v0
	v_mov_b32_e32 v63, v0
	v_mov_b32_e32 v64, v0
	v_mov_b32_e32 v65, v0
	v_mov_b32_e32 v66, v0
	v_mov_b32_e32 v67, v0
	v_mov_b32_e32 v68, v0
	v_mov_b32_e32 v69, v0
	v_mov_b32_e32 v70, v0
	v_mov_b32_e32 v71, v0
	v_mov_b32_e32 v80, v0
	v_mov_b32_e32 v81, v0
	v_mov_b32_e32 v82, v0
	v_mov_b32_e32 v83, v0
	v_mov_b32_e32 v84, v0
	v_mov_b32_e32 v85, v0
	v_mov_b32_e32 v86, v0
	v_mov_b32_e32 v87, v0
	v_mov_b32_e32 v96, v0
	v_mov_b32_e32 v97, v0
	v_mov_b32_e32 v98, v0
	v_mov_b32_e32 v99, v0
	v_mov_b32_e32 v100, v0
	v_mov_b32_e32 v101, v0
	v_mov_b32_e32 v102, v0
	v_mov_b32_e32 v103, v0
	v_mov_b32_e32 v112, v0
	v_mov_b32_e32 v113, v0
	v_mov_b32_e32 v114, v0
	v_mov_b32_e32 v115, v0
	v_mov_b32_e32 v116, v0
	v_mov_b32_e32 v117, v0
	v_mov_b32_e32 v118, v0
	v_mov_b32_e32 v119, v0
	v_mov_b32_e32 v72, v0
	v_mov_b32_e32 v73, v0
	v_mov_b32_e32 v74, v0
	v_mov_b32_e32 v75, v0
	v_mov_b32_e32 v76, v0
	v_mov_b32_e32 v77, v0
	v_mov_b32_e32 v78, v0
	v_mov_b32_e32 v79, v0
	v_mov_b32_e32 v88, v0
	v_mov_b32_e32 v89, v0
	v_mov_b32_e32 v90, v0
	v_mov_b32_e32 v91, v0
	v_mov_b32_e32 v92, v0
	v_mov_b32_e32 v93, v0
	v_mov_b32_e32 v94, v0
	v_mov_b32_e32 v95, v0
	v_mov_b32_e32 v104, v0
	v_mov_b32_e32 v105, v0
	v_mov_b32_e32 v106, v0
	v_mov_b32_e32 v107, v0
	v_mov_b32_e32 v108, v0
	v_mov_b32_e32 v109, v0
	v_mov_b32_e32 v110, v0
	v_mov_b32_e32 v111, v0
	v_mov_b32_e32 v120, v0
	v_mov_b32_e32 v121, v0
	v_mov_b32_e32 v122, v0
	v_mov_b32_e32 v123, v0
	v_mov_b32_e32 v124, v0
	v_mov_b32_e32 v125, v0
	v_mov_b32_e32 v126, v0
	v_mov_b32_e32 v127, v0
	v_readlane_b32 s98, v255, 17
	s_cmp_lg_u32 s98, 0
	s_cbranch_scc1 .Lsprio_5
	s_setprio 1

;     __host__ __device__ bool next(int i, Unit& u) const { return at((long)i * G + c, u); }
;     __host__ __device__ bool next(int i, Unit& u) const { if (i != 0 || c >= cnt) return false; u.pm = pm0 + c / nN; u.pn = c % nN; u.k0 = 0; u.nt = ntk; return true; }
;     ...
;         const bool has_next = S.next(ui + 1, nxt);
;         const char* nA = has_next ? (const char*)g.A + (size_t)nxt.pm * tstep + (size_t)nxt.k0 * (BK * 2) : cA; const char* nB = has_next ? (const char*)g.Bt + (size_t)nxt.pn * tstep + (size_t)nxt.k0 * (BK * 2) : cB;
;         const int nt = cur.nt;
;         for (int t = 0; t < nt; t += 2) {
;             const bool last = (t == nt - 2);
;             const char* a1 = cA + (size_t)(t + 1) * kstep;
;             const char* a2 = last ? nA : cA + (size_t)(t + 2) * kstep; const char* b2 = last ? nB : cB + (size_t)(t + 2) * kstep;
;             const char* a3 = a2 + kstep; const char* b3 = b2 + kstep;
.LBB0_1053:
	s_ashr_i32 s23, s22, 31
	s_xor_b64 s[28:29], s[40:41], -1
	s_lshl_b64 s[30:31], s[22:23], 21
	s_add_u32 s13, s4, s30
	s_addc_u32 s23, s5, s31
	s_ashr_i32 s27, s26, 31
	s_lshl_b64 s[34:35], s[26:27], 7
	s_add_u32 s30, s13, s34
	s_addc_u32 s31, s23, s35
	s_and_b64 s[42:43], s[40:41], exec
	s_cselect_b32 s13, s31, s39
	s_cselect_b32 s23, s30, s38
	s_ashr_i32 s25, s24, 31
	s_lshl_b64 s[42:43], s[24:25], 21
	s_add_u32 s25, s3, s42
	s_addc_u32 s27, s47, s43
	s_add_u32 s34, s25, s34
	s_addc_u32 s35, s27, s35
	s_and_b64 s[42:43], s[40:41], exec
	s_cselect_b32 s25, s35, s37
	s_cselect_b32 s27, s34, s36
	s_mov_b32 s73, 2
	s_mov_b64 s[42:43], 0x100
	v_mov_b64_e32 v[130:131], v[144:145]
	v_mov_b64_e32 v[150:151], v[142:143]
	v_readlane_b32 s98, v255, 17
	s_cmp_lg_u32 s98, 0
	s_cbranch_scc1 .Lsprio_6
	s_setprio 1
